# v011 + P7 (down-proj) epilogue: all 16 x1 residual loads prefetched into dead VGPRs at the epilogue top; 12 in-loop vmcnt waits (which also waited on the ssq atomics) removed
# baseline (speedup 1.0000x reference)
; __device__ __forceinline__ u32x4 pack8(f32x4 a, f32x4 b) { u32x4 w; w.x = cvt_pk_bf16(a[0], a[1]); w.y = cvt_pk_bf16(a[2], a[3]); w.z = cvt_pk_bf16(b[0], b[1]); w.w = cvt_pk_bf16(b[2], b[3]); return w; }
; __device__ __forceinline__ void atomic_addf(float* p, float v) { __hip_atomic_fetch_add(p, v, __ATOMIC_RELAXED, __HIP_MEMORY_SCOPE_AGENT); }
;     __device__ __forceinline__ void operator()(const f32x4 (&acc)[2][2][4][2], const Unit& u, int wr, int wc, int fr, int fq) const {
;         const int col0 = u.pn * BM + wc * 32 + 8 * fq;
;         const int rowb = u.pm * BM + wr * 64 + fr;
;         const bf16_t* ob = X1B + (size_t)rowb * DM + col0;
;         u32x4 xc[2], xn[2];
; #pragma unroll
;         for (int q = 0; q < 2; ++q) xc[q] = *(const u32x4*)(ob + q * HALF);
; #pragma unroll
;         for (int it = 0; it < 8; ++it) {
;             const int ai = it >> 2, m = it & 3;
;             if (it < 7) { const int a2 = (it + 1) >> 2, m2 = (it + 1) & 3;
; #pragma unroll
;                 for (int q = 0; q < 2; ++q) xn[q] = *(const u32x4*)(ob + (size_t)(a2 * HALF + m2 * 16) * DM + q * HALF); }
;             const int row = rowb + ai * HALF + m * 16;
;             bf16_t* orow = X1B + (size_t)row * DM + col0;
;             float ss = 0.f;
; #pragma unroll
;             for (int bj = 0; bj < 2; ++bj) {
;                 const u32x4 xw = xc[bj];
;                 const f32x4 v0 = (f32x4){bf_lo(xw.x), bf_hi(xw.x), bf_lo(xw.y), bf_hi(xw.y)} + acc[ai][bj][m][0], v1 = (f32x4){bf_lo(xw.z), bf_hi(xw.z), bf_lo(xw.w), bf_hi(xw.w)} + acc[ai][bj][m][1];
;                 ss += (v0[0] * v0[0] + v0[1] * v0[1]) + (v0[2] * v0[2] + v0[3] * v0[3]) + (v1[0] * v1[0] + v1[1] * v1[1]) + (v1[2] * v1[2] + v1[3] * v1[3]);
;                 *(u32x4*)(orow + bj * HALF) = pack8(v0, v1);
;             }
;             ss += __shfl_xor(ss, 16); ss += __shfl_xor(ss, 32);
;             if (fq == 0) atomic_addf(ssq3 + row, ss);
.LBB0_1143:
	v_lshl_add_u32 v156, s49, 8, v158
	v_ashrrev_i32_e32 v157, 31, v156
	v_lshl_or_b32 v152, s48, 8, v160
	v_lshlrev_b64 v[128:129], 12, v[156:157]
	v_lshl_add_u64 v[128:129], s[26:27], 0, v[128:129]
	v_ashrrev_i32_e32 v153, 31, v152
	v_lshl_add_u64 v[154:155], v[152:153], 1, v[128:129]
	global_load_dwordx4 v[166:169], v[154:155], off
	global_load_dwordx4 v[170:173], v[154:155], off offset:256
	v_add_co_u32_e32 v128, vcc, s56, v154
	v_and_b32_e32 v174, 64, v164
	s_nop 0
	v_addc_co_u32_e32 v129, vcc, 0, v155, vcc
	global_load_dwordx4 v[132:135], v[128:129], off
	s_nop 0
	global_load_dwordx4 v[128:131], v[128:129], off offset:256
	v_lshlrev_b32_e32 v236, 12, v156
	v_lshl_add_u32 v236, v152, 1, v236
	v_add_u32_e32 v237, 0x20000, v236
	global_load_dwordx4 v[184:187], v237, s[26:27]
	global_load_dwordx4 v[188:191], v237, s[26:27] offset:256
	v_add_u32_e32 v237, 0x30000, v236
	global_load_dwordx4 v[192:195], v237, s[26:27]
	global_load_dwordx4 v[196:199], v237, s[26:27] offset:256
	v_add_u32_e32 v237, 0x80000, v236
	global_load_dwordx4 v[200:203], v237, s[26:27]
	global_load_dwordx4 v[208:211], v237, s[26:27] offset:256
	v_add_u32_e32 v237, 0x90000, v236
	global_load_dwordx4 v[212:215], v237, s[26:27]
	global_load_dwordx4 v[216:219], v237, s[26:27] offset:256
	v_add_u32_e32 v237, 0xa0000, v236
	global_load_dwordx4 v[220:223], v237, s[26:27]
	global_load_dwordx4 v[224:227], v237, s[26:27] offset:256
	v_add_u32_e32 v237, 0xb0000, v236
	global_load_dwordx4 v[228:231], v237, s[26:27]
	global_load_dwordx4 v[232:235], v237, s[26:27] offset:256
	v_xor_b32_e32 v165, 16, v164
	v_add_u32_e32 v174, 64, v174
	v_xor_b32_e32 v175, 32, v164
	v_cmp_lt_i32_e32 vcc, v165, v174
	s_waitcnt vmcnt(0)
	v_lshlrev_b32_e32 v176, 16, v168
	v_cndmask_b32_e32 v165, v164, v165, vcc
	v_cmp_lt_i32_e32 vcc, v175, v174
	v_lshlrev_b32_e32 v174, 16, v166
	v_lshlrev_b32_e32 v178, 16, v170
	v_cndmask_b32_e32 v182, v164, v175, vcc
	v_and_b32_e32 v175, 0xffff0000, v166
	v_lshlrev_b32_e32 v166, 16, v167
	v_and_b32_e32 v167, 0xffff0000, v167
	v_and_b32_e32 v179, 0xffff0000, v170
	v_lshlrev_b32_e32 v170, 16, v171
	v_and_b32_e32 v171, 0xffff0000, v171
	v_and_b32_e32 v177, 0xffff0000, v168
	v_lshlrev_b32_e32 v168, 16, v169
	v_and_b32_e32 v169, 0xffff0000, v169
	v_lshlrev_b32_e32 v180, 16, v172
	v_and_b32_e32 v181, 0xffff0000, v172
	v_lshlrev_b32_e32 v172, 16, v173
	v_and_b32_e32 v173, 0xffff0000, v173
	v_pk_add_f32 v[126:127], v[126:127], v[166:167]
	v_pk_add_f32 v[124:125], v[124:125], v[174:175]
	v_pk_add_f32 v[118:119], v[118:119], v[170:171]
	v_pk_add_f32 v[116:117], v[116:117], v[178:179]
	v_pk_add_f32 v[122:123], v[122:123], v[168:169]
	v_pk_add_f32 v[120:121], v[120:121], v[176:177]
	v_pk_add_f32 v[166:167], v[114:115], v[172:173]
	v_pk_add_f32 v[168:169], v[112:113], v[180:181]
	v_mul_f32_e32 v114, v125, v125
	v_mul_f32_e32 v115, v127, v127
	v_cvt_pk_bf16_f32 v112, v124, v125
	v_cvt_pk_bf16_f32 v113, v126, v127
	v_mul_f32_e32 v125, v117, v117
	v_mul_f32_e32 v127, v119, v119
	v_mul_f32_e32 v170, v121, v121
	v_mul_f32_e32 v172, v169, v169
	v_fmac_f32_e32 v114, v124, v124
	v_fmac_f32_e32 v115, v126, v126
	v_fmac_f32_e32 v125, v116, v116
	v_fmac_f32_e32 v127, v118, v118
	v_mul_f32_e32 v171, v123, v123
	v_mul_f32_e32 v173, v167, v167
	v_fmac_f32_e32 v170, v120, v120
	v_fmac_f32_e32 v172, v168, v168
	v_add_f32_e32 v114, v114, v115
	v_add_f32_e32 v115, v125, v127
	v_fmac_f32_e32 v171, v122, v122
	v_fmac_f32_e32 v173, v166, v166
	v_add_f32_e32 v114, v170, v114
	v_add_f32_e32 v115, v172, v115
	v_add_f32_e32 v114, v171, v114
	v_add_f32_e32 v115, v173, v115
	v_lshlrev_b32_e32 v165, 2, v165
	v_add_f32_e32 v124, v114, v115
	ds_bpermute_b32 v125, v165, v124
	v_cvt_pk_bf16_f32 v114, v120, v121
	v_cvt_pk_bf16_f32 v115, v122, v123
	global_store_dwordx4 v[154:155], v[112:115], off
	v_lshlrev_b32_e32 v122, 2, v182
	s_waitcnt lgkmcnt(0)
	v_add_f32_e32 v112, v124, v125
	ds_bpermute_b32 v113, v122, v112
	v_cvt_pk_bf16_f32 v114, v116, v117
	v_cvt_pk_bf16_f32 v115, v118, v119
	v_cvt_pk_bf16_f32 v116, v168, v169
	v_cvt_pk_bf16_f32 v117, v166, v167
	global_store_dwordx4 v[154:155], v[114:117], off offset:256
	s_and_saveexec_b64 s[24:25], s[2:3]
	s_cbranch_execz .LBB0_1145
	s_waitcnt lgkmcnt(0)
	v_add_f32_e32 v114, v112, v113
	v_lshl_add_u64 v[112:113], v[156:157], 2, s[6:7]
	global_atomic_add_f32 v[112:113], v114, off
; __device__ __forceinline__ u32x4 pack8(f32x4 a, f32x4 b) { u32x4 w; w.x = cvt_pk_bf16(a[0], a[1]); w.y = cvt_pk_bf16(a[2], a[3]); w.z = cvt_pk_bf16(b[0], b[1]); w.w = cvt_pk_bf16(b[2], b[3]); return w; }
; __device__ __forceinline__ void atomic_addf(float* p, float v) { __hip_atomic_fetch_add(p, v, __ATOMIC_RELAXED, __HIP_MEMORY_SCOPE_AGENT); }
;     __device__ __forceinline__ void operator()(const f32x4 (&acc)[2][2][4][2], const Unit& u, int wr, int wc, int fr, int fq) const {
;     ...
;         for (int it = 0; it < 8; ++it) {
;             const int ai = it >> 2, m = it & 3;
;             if (it < 7) { const int a2 = (it + 1) >> 2, m2 = (it + 1) & 3;
; #pragma unroll
;                 for (int q = 0; q < 2; ++q) xn[q] = *(const u32x4*)(ob + (size_t)(a2 * HALF + m2 * 16) * DM + q * HALF); }
;             const int row = rowb + ai * HALF + m * 16;
;             bf16_t* orow = X1B + (size_t)row * DM + col0;
;             float ss = 0.f;
; #pragma unroll
;             for (int bj = 0; bj < 2; ++bj) {
;                 const u32x4 xw = xc[bj];
;                 const f32x4 v0 = (f32x4){bf_lo(xw.x), bf_hi(xw.x), bf_lo(xw.y), bf_hi(xw.y)} + acc[ai][bj][m][0], v1 = (f32x4){bf_lo(xw.z), bf_hi(xw.z), bf_lo(xw.w), bf_hi(xw.w)} + acc[ai][bj][m][1];
;                 ss += (v0[0] * v0[0] + v0[1] * v0[1]) + (v0[2] * v0[2] + v0[3] * v0[3]) + (v1[0] * v1[0] + v1[1] * v1[1]) + (v1[2] * v1[2] + v1[3] * v1[3]);
;                 *(u32x4*)(orow + bj * HALF) = pack8(v0, v1);
;             }
;             ss += __shfl_xor(ss, 16); ss += __shfl_xor(ss, 32);
;             if (fq == 0) atomic_addf(ssq3 + row, ss);
; #pragma unroll
;             for (int q = 0; q < 2; ++q) xc[q] = xn[q];
.LBB0_1145:
	s_or_b64 exec, exec, s[24:25]
	v_add_co_u32_e32 v112, vcc, 0x20000, v154
	v_lshlrev_b32_e32 v126, 16, v132
	s_waitcnt lgkmcnt(0)
	v_addc_co_u32_e32 v113, vcc, 0, v155, vcc
	v_mov_b32_e32 v116, v184
	v_mov_b32_e32 v117, v185
	v_mov_b32_e32 v118, v186
	v_mov_b32_e32 v119, v187
	v_mov_b32_e32 v112, v188
	v_mov_b32_e32 v113, v189
	v_mov_b32_e32 v114, v190
	v_mov_b32_e32 v115, v191
	v_and_b32_e32 v127, 0xffff0000, v132
	v_lshlrev_b32_e32 v132, 16, v133
	v_and_b32_e32 v133, 0xffff0000, v133
	v_pk_add_f32 v[110:111], v[110:111], v[132:133]
	v_pk_add_f32 v[108:109], v[108:109], v[126:127]
	v_lshlrev_b32_e32 v126, 16, v134
	v_and_b32_e32 v127, 0xffff0000, v134
	v_lshlrev_b32_e32 v132, 16, v135
	v_and_b32_e32 v133, 0xffff0000, v135
	v_pk_add_f32 v[132:133], v[106:107], v[132:133]
	v_pk_add_f32 v[106:107], v[104:105], v[126:127]
	v_mul_f32_e32 v104, v109, v109
	v_mul_f32_e32 v105, v111, v111
	v_fmac_f32_e32 v104, v108, v108
	v_fmac_f32_e32 v105, v110, v110
	v_add_f32_e32 v104, v104, v105
	v_mul_f32_e32 v105, v107, v107
	v_fmac_f32_e32 v105, v106, v106
	v_add_f32_e32 v104, v105, v104
	v_mul_f32_e32 v105, v133, v133
	v_fmac_f32_e32 v105, v132, v132
	v_add_f32_e32 v123, v105, v104
	v_cvt_pk_bf16_f32 v104, v108, v109
	v_cvt_pk_bf16_f32 v105, v110, v111
	v_lshlrev_b32_e32 v108, 16, v128
	v_and_b32_e32 v109, 0xffff0000, v128
	v_lshlrev_b32_e32 v110, 16, v129
	v_and_b32_e32 v111, 0xffff0000, v129
	v_pk_add_f32 v[102:103], v[102:103], v[110:111]
	v_pk_add_f32 v[100:101], v[100:101], v[108:109]
	v_lshlrev_b32_e32 v108, 16, v130
	v_and_b32_e32 v109, 0xffff0000, v130
	v_pk_add_f32 v[108:109], v[96:97], v[108:109]
	v_mul_f32_e32 v96, v101, v101
	v_mul_f32_e32 v97, v103, v103
	v_fmac_f32_e32 v96, v100, v100
	v_fmac_f32_e32 v97, v102, v102
	v_lshlrev_b32_e32 v110, 16, v131
	v_and_b32_e32 v111, 0xffff0000, v131
	v_add_f32_e32 v96, v96, v97
	v_mul_f32_e32 v97, v109, v109
	v_pk_add_f32 v[110:111], v[98:99], v[110:111]
	v_fmac_f32_e32 v97, v108, v108
	v_add_f32_e32 v96, v97, v96
	v_mul_f32_e32 v97, v111, v111
	v_fmac_f32_e32 v97, v110, v110
	v_add_f32_e32 v96, v97, v96
	v_add_f32_e32 v96, v123, v96
	ds_bpermute_b32 v97, v165, v96
	v_or_b32_e32 v120, 16, v156
	v_ashrrev_i32_e32 v121, 31, v120
	v_lshlrev_b64 v[124:125], 12, v[120:121]
	v_lshl_add_u64 v[124:125], s[26:27], 0, v[124:125]
	s_waitcnt lgkmcnt(0)
	v_add_f32_e32 v96, v96, v97
	ds_bpermute_b32 v97, v122, v96
	v_lshl_add_u64 v[124:125], v[152:153], 1, v[124:125]
	v_cvt_pk_bf16_f32 v106, v106, v107
	v_cvt_pk_bf16_f32 v107, v132, v133
	global_store_dwordx4 v[124:125], v[104:107], off
	v_cvt_pk_bf16_f32 v98, v100, v101
	v_cvt_pk_bf16_f32 v99, v102, v103
	v_cvt_pk_bf16_f32 v100, v108, v109
	v_cvt_pk_bf16_f32 v101, v110, v111
	global_store_dwordx4 v[124:125], v[98:101], off offset:256
	s_and_saveexec_b64 s[24:25], s[2:3]
	s_cbranch_execz .LBB0_1147
	s_waitcnt lgkmcnt(0)
	v_add_f32_e32 v98, v96, v97
	v_lshl_add_u64 v[96:97], v[120:121], 2, s[6:7]
	global_atomic_add_f32 v[96:97], v98, off
.LBB0_1147:
	s_or_b64 exec, exec, s[24:25]
	v_add_co_u32_e32 v96, vcc, 0x30000, v154
	v_lshlrev_b32_e32 v108, 16, v116
	s_waitcnt lgkmcnt(0)
	v_addc_co_u32_e32 v97, vcc, 0, v155, vcc
	v_mov_b32_e32 v100, v192
	v_mov_b32_e32 v101, v193
	v_mov_b32_e32 v102, v194
	v_mov_b32_e32 v103, v195
	v_mov_b32_e32 v96, v196
	v_mov_b32_e32 v97, v197
	v_mov_b32_e32 v98, v198
	v_mov_b32_e32 v99, v199
	v_and_b32_e32 v109, 0xffff0000, v116
	v_lshlrev_b32_e32 v110, 16, v117
	v_and_b32_e32 v111, 0xffff0000, v117
	v_pk_add_f32 v[94:95], v[94:95], v[110:111]
	v_pk_add_f32 v[92:93], v[92:93], v[108:109]
	v_lshlrev_b32_e32 v108, 16, v118
	v_and_b32_e32 v109, 0xffff0000, v118
	v_lshlrev_b32_e32 v110, 16, v119
	v_and_b32_e32 v111, 0xffff0000, v119
	v_pk_add_f32 v[110:111], v[90:91], v[110:111]
	v_pk_add_f32 v[90:91], v[88:89], v[108:109]
	v_mul_f32_e32 v88, v93, v93
	v_mul_f32_e32 v89, v95, v95
	v_fmac_f32_e32 v88, v92, v92
	v_fmac_f32_e32 v89, v94, v94
	v_add_f32_e32 v88, v88, v89
	v_mul_f32_e32 v89, v91, v91
	v_fmac_f32_e32 v89, v90, v90
	v_add_f32_e32 v88, v89, v88
	v_mul_f32_e32 v89, v111, v111
	v_fmac_f32_e32 v89, v110, v110
	v_add_f32_e32 v108, v89, v88
	v_cvt_pk_bf16_f32 v88, v92, v93
	v_cvt_pk_bf16_f32 v89, v94, v95
	v_lshlrev_b32_e32 v92, 16, v112
	v_and_b32_e32 v93, 0xffff0000, v112
	v_lshlrev_b32_e32 v94, 16, v113
	v_and_b32_e32 v95, 0xffff0000, v113
	v_pk_add_f32 v[86:87], v[86:87], v[94:95]
	v_pk_add_f32 v[84:85], v[84:85], v[92:93]
	v_lshlrev_b32_e32 v92, 16, v114
	v_and_b32_e32 v93, 0xffff0000, v114
	v_pk_add_f32 v[92:93], v[80:81], v[92:93]
	v_mul_f32_e32 v80, v85, v85
	v_mul_f32_e32 v81, v87, v87
	v_fmac_f32_e32 v80, v84, v84
	v_fmac_f32_e32 v81, v86, v86
	v_lshlrev_b32_e32 v94, 16, v115
	v_and_b32_e32 v95, 0xffff0000, v115
	v_add_f32_e32 v80, v80, v81
	v_mul_f32_e32 v81, v93, v93
	v_pk_add_f32 v[94:95], v[82:83], v[94:95]
	v_fmac_f32_e32 v81, v92, v92
	v_add_f32_e32 v80, v81, v80
	v_mul_f32_e32 v81, v95, v95
	v_fmac_f32_e32 v81, v94, v94
	v_add_f32_e32 v80, v81, v80
	v_add_f32_e32 v80, v108, v80
	ds_bpermute_b32 v81, v165, v80
	v_or_b32_e32 v104, 32, v156
	v_ashrrev_i32_e32 v105, 31, v104
	v_lshlrev_b64 v[106:107], 12, v[104:105]
	v_lshl_add_u64 v[106:107], s[26:27], 0, v[106:107]
	s_waitcnt lgkmcnt(0)
	v_add_f32_e32 v80, v80, v81
	ds_bpermute_b32 v81, v122, v80
	v_lshl_add_u64 v[106:107], v[152:153], 1, v[106:107]
	v_cvt_pk_bf16_f32 v90, v90, v91
	v_cvt_pk_bf16_f32 v91, v110, v111
	global_store_dwordx4 v[106:107], v[88:91], off
	v_cvt_pk_bf16_f32 v82, v84, v85
	v_cvt_pk_bf16_f32 v83, v86, v87
	v_cvt_pk_bf16_f32 v84, v92, v93
	v_cvt_pk_bf16_f32 v85, v94, v95
	global_store_dwordx4 v[106:107], v[82:85], off offset:256
	s_and_saveexec_b64 s[24:25], s[2:3]
	s_cbranch_execz .LBB0_1149
	s_waitcnt lgkmcnt(0)
	v_add_f32_e32 v82, v80, v81
	v_lshl_add_u64 v[80:81], v[104:105], 2, s[6:7]
	global_atomic_add_f32 v[80:81], v82, off
; __device__ __forceinline__ u32x4 pack8(f32x4 a, f32x4 b) { u32x4 w; w.x = cvt_pk_bf16(a[0], a[1]); w.y = cvt_pk_bf16(a[2], a[3]); w.z = cvt_pk_bf16(b[0], b[1]); w.w = cvt_pk_bf16(b[2], b[3]); return w; }
; __device__ __forceinline__ void atomic_addf(float* p, float v) { __hip_atomic_fetch_add(p, v, __ATOMIC_RELAXED, __HIP_MEMORY_SCOPE_AGENT); }
;     __device__ __forceinline__ void operator()(const f32x4 (&acc)[2][2][4][2], const Unit& u, int wr, int wc, int fr, int fq) const {
;     ...
;         for (int it = 0; it < 8; ++it) {
;             const int ai = it >> 2, m = it & 3;
;             if (it < 7) { const int a2 = (it + 1) >> 2, m2 = (it + 1) & 3;
; #pragma unroll
;                 for (int q = 0; q < 2; ++q) xn[q] = *(const u32x4*)(ob + (size_t)(a2 * HALF + m2 * 16) * DM + q * HALF); }
;             const int row = rowb + ai * HALF + m * 16;
;             bf16_t* orow = X1B + (size_t)row * DM + col0;
;             float ss = 0.f;
; #pragma unroll
;             for (int bj = 0; bj < 2; ++bj) {
;                 const u32x4 xw = xc[bj];
;                 const f32x4 v0 = (f32x4){bf_lo(xw.x), bf_hi(xw.x), bf_lo(xw.y), bf_hi(xw.y)} + acc[ai][bj][m][0], v1 = (f32x4){bf_lo(xw.z), bf_hi(xw.z), bf_lo(xw.w), bf_hi(xw.w)} + acc[ai][bj][m][1];
;                 ss += (v0[0] * v0[0] + v0[1] * v0[1]) + (v0[2] * v0[2] + v0[3] * v0[3]) + (v1[0] * v1[0] + v1[1] * v1[1]) + (v1[2] * v1[2] + v1[3] * v1[3]);
;                 *(u32x4*)(orow + bj * HALF) = pack8(v0, v1);
;             }
;             ss += __shfl_xor(ss, 16); ss += __shfl_xor(ss, 32);
;             if (fq == 0) atomic_addf(ssq3 + row, ss);
; #pragma unroll
;             for (int q = 0; q < 2; ++q) xc[q] = xn[q];
;             __builtin_amdgcn_sched_barrier(0);
;         }
.LBB0_1149:
	s_or_b64 exec, exec, s[24:25]
	v_add_co_u32_e32 v80, vcc, 0x80000, v154
	v_lshlrev_b32_e32 v92, 16, v100
	s_waitcnt lgkmcnt(0)
	v_addc_co_u32_e32 v81, vcc, 0, v155, vcc
	v_mov_b32_e32 v84, v200
	v_mov_b32_e32 v85, v201
	v_mov_b32_e32 v86, v202
	v_mov_b32_e32 v87, v203
	v_mov_b32_e32 v80, v208
	v_mov_b32_e32 v81, v209
	v_mov_b32_e32 v82, v210
	v_mov_b32_e32 v83, v211
	v_and_b32_e32 v93, 0xffff0000, v100
	v_lshlrev_b32_e32 v94, 16, v101
	v_and_b32_e32 v95, 0xffff0000, v101
	v_pk_add_f32 v[78:79], v[78:79], v[94:95]
	v_pk_add_f32 v[76:77], v[76:77], v[92:93]
	v_lshlrev_b32_e32 v92, 16, v102
	v_and_b32_e32 v93, 0xffff0000, v102
	v_lshlrev_b32_e32 v94, 16, v103
	v_and_b32_e32 v95, 0xffff0000, v103
	v_pk_add_f32 v[94:95], v[74:75], v[94:95]
	v_pk_add_f32 v[74:75], v[72:73], v[92:93]
	v_mul_f32_e32 v72, v77, v77
	v_mul_f32_e32 v73, v79, v79
	v_fmac_f32_e32 v72, v76, v76
	v_fmac_f32_e32 v73, v78, v78
	v_add_f32_e32 v72, v72, v73
	v_mul_f32_e32 v73, v75, v75
	v_fmac_f32_e32 v73, v74, v74
	v_add_f32_e32 v72, v73, v72
	v_mul_f32_e32 v73, v95, v95
	v_fmac_f32_e32 v73, v94, v94
	v_add_f32_e32 v92, v73, v72
	v_cvt_pk_bf16_f32 v72, v76, v77
	v_cvt_pk_bf16_f32 v73, v78, v79
	v_lshlrev_b32_e32 v76, 16, v96
	v_and_b32_e32 v77, 0xffff0000, v96
	v_lshlrev_b32_e32 v78, 16, v97
	v_and_b32_e32 v79, 0xffff0000, v97
	v_pk_add_f32 v[70:71], v[70:71], v[78:79]
	v_pk_add_f32 v[68:69], v[68:69], v[76:77]
	v_lshlrev_b32_e32 v76, 16, v98
	v_and_b32_e32 v77, 0xffff0000, v98
	v_pk_add_f32 v[76:77], v[64:65], v[76:77]
	v_mul_f32_e32 v64, v69, v69
	v_mul_f32_e32 v65, v71, v71
	v_fmac_f32_e32 v64, v68, v68
	v_fmac_f32_e32 v65, v70, v70
	v_lshlrev_b32_e32 v78, 16, v99
	v_and_b32_e32 v79, 0xffff0000, v99
	v_add_f32_e32 v64, v64, v65
	v_mul_f32_e32 v65, v77, v77
	v_pk_add_f32 v[78:79], v[66:67], v[78:79]
	v_fmac_f32_e32 v65, v76, v76
	v_add_f32_e32 v64, v65, v64
	v_mul_f32_e32 v65, v79, v79
	v_fmac_f32_e32 v65, v78, v78
	v_add_f32_e32 v64, v65, v64
	v_add_f32_e32 v64, v92, v64
	ds_bpermute_b32 v65, v165, v64
	v_or_b32_e32 v88, 48, v156
	v_ashrrev_i32_e32 v89, 31, v88
	v_lshlrev_b64 v[90:91], 12, v[88:89]
	v_lshl_add_u64 v[90:91], s[26:27], 0, v[90:91]
	s_waitcnt lgkmcnt(0)
	v_add_f32_e32 v64, v64, v65
	ds_bpermute_b32 v65, v122, v64
	v_lshl_add_u64 v[90:91], v[152:153], 1, v[90:91]
	v_cvt_pk_bf16_f32 v74, v74, v75
	v_cvt_pk_bf16_f32 v75, v94, v95
	global_store_dwordx4 v[90:91], v[72:75], off
	v_cvt_pk_bf16_f32 v66, v68, v69
	v_cvt_pk_bf16_f32 v67, v70, v71
	v_cvt_pk_bf16_f32 v68, v76, v77
	v_cvt_pk_bf16_f32 v69, v78, v79
	global_store_dwordx4 v[90:91], v[66:69], off offset:256
	s_and_saveexec_b64 s[24:25], s[2:3]
	s_cbranch_execz .LBB0_1151
	s_waitcnt lgkmcnt(0)
	v_add_f32_e32 v66, v64, v65
	v_lshl_add_u64 v[64:65], v[88:89], 2, s[6:7]
	global_atomic_add_f32 v[64:65], v66, off
.LBB0_1151:
	s_or_b64 exec, exec, s[24:25]
	v_add_co_u32_e32 v64, vcc, 0x90000, v154
	v_lshlrev_b32_e32 v76, 16, v84
	s_waitcnt lgkmcnt(0)
	v_addc_co_u32_e32 v65, vcc, 0, v155, vcc
	v_mov_b32_e32 v68, v212
	v_mov_b32_e32 v69, v213
	v_mov_b32_e32 v70, v214
	v_mov_b32_e32 v71, v215
	v_mov_b32_e32 v64, v216
	v_mov_b32_e32 v65, v217
	v_mov_b32_e32 v66, v218
	v_mov_b32_e32 v67, v219
	v_and_b32_e32 v77, 0xffff0000, v84
	v_lshlrev_b32_e32 v78, 16, v85
	v_and_b32_e32 v79, 0xffff0000, v85
	v_pk_add_f32 v[62:63], v[62:63], v[78:79]
	v_pk_add_f32 v[60:61], v[60:61], v[76:77]
	v_lshlrev_b32_e32 v76, 16, v86
	v_and_b32_e32 v77, 0xffff0000, v86
	v_lshlrev_b32_e32 v78, 16, v87
	v_and_b32_e32 v79, 0xffff0000, v87
	v_pk_add_f32 v[78:79], v[58:59], v[78:79]
	v_pk_add_f32 v[58:59], v[56:57], v[76:77]
	v_mul_f32_e32 v56, v61, v61
	v_mul_f32_e32 v57, v63, v63
	v_fmac_f32_e32 v56, v60, v60
	v_fmac_f32_e32 v57, v62, v62
	v_add_f32_e32 v56, v56, v57
	v_mul_f32_e32 v57, v59, v59
	v_fmac_f32_e32 v57, v58, v58
	v_add_f32_e32 v56, v57, v56
	v_mul_f32_e32 v57, v79, v79
	v_fmac_f32_e32 v57, v78, v78
	v_add_f32_e32 v76, v57, v56
	v_cvt_pk_bf16_f32 v56, v60, v61
	v_cvt_pk_bf16_f32 v57, v62, v63
	v_lshlrev_b32_e32 v60, 16, v80
	v_and_b32_e32 v61, 0xffff0000, v80
	v_lshlrev_b32_e32 v62, 16, v81
	v_and_b32_e32 v63, 0xffff0000, v81
	v_pk_add_f32 v[54:55], v[54:55], v[62:63]
	v_pk_add_f32 v[52:53], v[52:53], v[60:61]
	v_lshlrev_b32_e32 v60, 16, v82
	v_and_b32_e32 v61, 0xffff0000, v82
	v_pk_add_f32 v[60:61], v[48:49], v[60:61]
	v_mul_f32_e32 v48, v53, v53
	v_mul_f32_e32 v49, v55, v55
	v_fmac_f32_e32 v48, v52, v52
	v_fmac_f32_e32 v49, v54, v54
	v_lshlrev_b32_e32 v62, 16, v83
	v_and_b32_e32 v63, 0xffff0000, v83
	v_add_f32_e32 v48, v48, v49
	v_mul_f32_e32 v49, v61, v61
	v_pk_add_f32 v[62:63], v[50:51], v[62:63]
	v_fmac_f32_e32 v49, v60, v60
	v_add_f32_e32 v48, v49, v48
	v_mul_f32_e32 v49, v63, v63
	v_fmac_f32_e32 v49, v62, v62
	v_add_f32_e32 v48, v49, v48
	v_add_f32_e32 v48, v76, v48
	ds_bpermute_b32 v49, v165, v48
	v_add_u32_e32 v72, 0x80, v156
	v_ashrrev_i32_e32 v73, 31, v72
	v_lshlrev_b64 v[74:75], 12, v[72:73]
	v_lshl_add_u64 v[74:75], s[26:27], 0, v[74:75]
	s_waitcnt lgkmcnt(0)
	v_add_f32_e32 v48, v48, v49
	ds_bpermute_b32 v49, v122, v48
	v_lshl_add_u64 v[74:75], v[152:153], 1, v[74:75]
	v_cvt_pk_bf16_f32 v58, v58, v59
	v_cvt_pk_bf16_f32 v59, v78, v79
	global_store_dwordx4 v[74:75], v[56:59], off
	v_cvt_pk_bf16_f32 v50, v52, v53
	v_cvt_pk_bf16_f32 v51, v54, v55
	v_cvt_pk_bf16_f32 v52, v60, v61
	v_cvt_pk_bf16_f32 v53, v62, v63
	global_store_dwordx4 v[74:75], v[50:53], off offset:256
	s_and_saveexec_b64 s[24:25], s[2:3]
	s_cbranch_execz .LBB0_1153
	s_waitcnt lgkmcnt(0)
	v_add_f32_e32 v50, v48, v49
	v_lshl_add_u64 v[48:49], v[72:73], 2, s[6:7]
	global_atomic_add_f32 v[48:49], v50, off
; __device__ __forceinline__ u32x4 pack8(f32x4 a, f32x4 b) { u32x4 w; w.x = cvt_pk_bf16(a[0], a[1]); w.y = cvt_pk_bf16(a[2], a[3]); w.z = cvt_pk_bf16(b[0], b[1]); w.w = cvt_pk_bf16(b[2], b[3]); return w; }
; __device__ __forceinline__ void atomic_addf(float* p, float v) { __hip_atomic_fetch_add(p, v, __ATOMIC_RELAXED, __HIP_MEMORY_SCOPE_AGENT); }
;     __device__ __forceinline__ void operator()(const f32x4 (&acc)[2][2][4][2], const Unit& u, int wr, int wc, int fr, int fq) const {
;     ...
;         for (int it = 0; it < 8; ++it) {
;             const int ai = it >> 2, m = it & 3;
;             if (it < 7) { const int a2 = (it + 1) >> 2, m2 = (it + 1) & 3;
; #pragma unroll
;                 for (int q = 0; q < 2; ++q) xn[q] = *(const u32x4*)(ob + (size_t)(a2 * HALF + m2 * 16) * DM + q * HALF); }
;             const int row = rowb + ai * HALF + m * 16;
;             bf16_t* orow = X1B + (size_t)row * DM + col0;
;             float ss = 0.f;
; #pragma unroll
;             for (int bj = 0; bj < 2; ++bj) {
;                 const u32x4 xw = xc[bj];
;                 const f32x4 v0 = (f32x4){bf_lo(xw.x), bf_hi(xw.x), bf_lo(xw.y), bf_hi(xw.y)} + acc[ai][bj][m][0], v1 = (f32x4){bf_lo(xw.z), bf_hi(xw.z), bf_lo(xw.w), bf_hi(xw.w)} + acc[ai][bj][m][1];
;                 ss += (v0[0] * v0[0] + v0[1] * v0[1]) + (v0[2] * v0[2] + v0[3] * v0[3]) + (v1[0] * v1[0] + v1[1] * v1[1]) + (v1[2] * v1[2] + v1[3] * v1[3]);
;                 *(u32x4*)(orow + bj * HALF) = pack8(v0, v1);
;             }
;             ss += __shfl_xor(ss, 16); ss += __shfl_xor(ss, 32);
;             if (fq == 0) atomic_addf(ssq3 + row, ss);
; #pragma unroll
;             for (int q = 0; q < 2; ++q) xc[q] = xn[q];
;             __builtin_amdgcn_sched_barrier(0);
;         }
.LBB0_1153:
	s_or_b64 exec, exec, s[24:25]
	v_add_co_u32_e32 v48, vcc, 0xa0000, v154
	v_lshlrev_b32_e32 v60, 16, v68
	s_waitcnt lgkmcnt(0)
	v_addc_co_u32_e32 v49, vcc, 0, v155, vcc
	v_mov_b32_e32 v52, v220
	v_mov_b32_e32 v53, v221
	v_mov_b32_e32 v54, v222
	v_mov_b32_e32 v55, v223
	v_mov_b32_e32 v48, v224
	v_mov_b32_e32 v49, v225
	v_mov_b32_e32 v50, v226
	v_mov_b32_e32 v51, v227
	v_and_b32_e32 v61, 0xffff0000, v68
	v_lshlrev_b32_e32 v62, 16, v69
	v_and_b32_e32 v63, 0xffff0000, v69
	v_pk_add_f32 v[46:47], v[46:47], v[62:63]
	v_pk_add_f32 v[44:45], v[44:45], v[60:61]
	v_lshlrev_b32_e32 v60, 16, v70
	v_and_b32_e32 v61, 0xffff0000, v70
	v_lshlrev_b32_e32 v62, 16, v71
	v_and_b32_e32 v63, 0xffff0000, v71
	v_pk_add_f32 v[62:63], v[42:43], v[62:63]
	v_pk_add_f32 v[42:43], v[40:41], v[60:61]
	v_mul_f32_e32 v40, v45, v45
	v_mul_f32_e32 v41, v47, v47
	v_fmac_f32_e32 v40, v44, v44
	v_fmac_f32_e32 v41, v46, v46
	v_add_f32_e32 v40, v40, v41
	v_mul_f32_e32 v41, v43, v43
	v_fmac_f32_e32 v41, v42, v42
	v_add_f32_e32 v40, v41, v40
	v_mul_f32_e32 v41, v63, v63
	v_fmac_f32_e32 v41, v62, v62
	v_add_f32_e32 v60, v41, v40
	v_cvt_pk_bf16_f32 v40, v44, v45
	v_cvt_pk_bf16_f32 v41, v46, v47
	v_lshlrev_b32_e32 v44, 16, v64
	v_and_b32_e32 v45, 0xffff0000, v64
	v_lshlrev_b32_e32 v46, 16, v65
	v_and_b32_e32 v47, 0xffff0000, v65
	v_pk_add_f32 v[38:39], v[38:39], v[46:47]
	v_pk_add_f32 v[36:37], v[36:37], v[44:45]
	v_lshlrev_b32_e32 v44, 16, v66
	v_and_b32_e32 v45, 0xffff0000, v66
	v_pk_add_f32 v[44:45], v[32:33], v[44:45]
	v_mul_f32_e32 v32, v37, v37
	v_mul_f32_e32 v33, v39, v39
	v_fmac_f32_e32 v32, v36, v36
	v_fmac_f32_e32 v33, v38, v38
	v_lshlrev_b32_e32 v46, 16, v67
	v_and_b32_e32 v47, 0xffff0000, v67
	v_add_f32_e32 v32, v32, v33
	v_mul_f32_e32 v33, v45, v45
	v_pk_add_f32 v[46:47], v[34:35], v[46:47]
	v_fmac_f32_e32 v33, v44, v44
	v_add_f32_e32 v32, v33, v32
	v_mul_f32_e32 v33, v47, v47
	v_fmac_f32_e32 v33, v46, v46
	v_add_f32_e32 v32, v33, v32
	v_add_f32_e32 v32, v60, v32
	ds_bpermute_b32 v33, v165, v32
	v_or_b32_e32 v56, 16, v72
	v_ashrrev_i32_e32 v57, 31, v56
	v_lshlrev_b64 v[58:59], 12, v[56:57]
	v_lshl_add_u64 v[58:59], s[26:27], 0, v[58:59]
	s_waitcnt lgkmcnt(0)
	v_add_f32_e32 v32, v32, v33
	ds_bpermute_b32 v33, v122, v32
	v_lshl_add_u64 v[58:59], v[152:153], 1, v[58:59]
	v_cvt_pk_bf16_f32 v42, v42, v43
	v_cvt_pk_bf16_f32 v43, v62, v63
	global_store_dwordx4 v[58:59], v[40:43], off
	v_cvt_pk_bf16_f32 v34, v36, v37
	v_cvt_pk_bf16_f32 v35, v38, v39
	v_cvt_pk_bf16_f32 v36, v44, v45
	v_cvt_pk_bf16_f32 v37, v46, v47
	global_store_dwordx4 v[58:59], v[34:37], off offset:256
	s_and_saveexec_b64 s[24:25], s[2:3]
	s_cbranch_execz .LBB0_1155
	s_waitcnt lgkmcnt(0)
	v_add_f32_e32 v34, v32, v33
	v_lshl_add_u64 v[32:33], v[56:57], 2, s[6:7]
	global_atomic_add_f32 v[32:33], v34, off
; __device__ __forceinline__ u32x4 pack8(f32x4 a, f32x4 b) { u32x4 w; w.x = cvt_pk_bf16(a[0], a[1]); w.y = cvt_pk_bf16(a[2], a[3]); w.z = cvt_pk_bf16(b[0], b[1]); w.w = cvt_pk_bf16(b[2], b[3]); return w; }
; __device__ __forceinline__ void atomic_addf(float* p, float v) { __hip_atomic_fetch_add(p, v, __ATOMIC_RELAXED, __HIP_MEMORY_SCOPE_AGENT); }
;     __device__ __forceinline__ void operator()(const f32x4 (&acc)[2][2][4][2], const Unit& u, int wr, int wc, int fr, int fq) const {
;     ...
;         for (int it = 0; it < 8; ++it) {
;             const int ai = it >> 2, m = it & 3;
;             if (it < 7) { const int a2 = (it + 1) >> 2, m2 = (it + 1) & 3;
; #pragma unroll
;                 for (int q = 0; q < 2; ++q) xn[q] = *(const u32x4*)(ob + (size_t)(a2 * HALF + m2 * 16) * DM + q * HALF); }
;             const int row = rowb + ai * HALF + m * 16;
;             bf16_t* orow = X1B + (size_t)row * DM + col0;
;             float ss = 0.f;
; #pragma unroll
;             for (int bj = 0; bj < 2; ++bj) {
;                 const u32x4 xw = xc[bj];
;                 const f32x4 v0 = (f32x4){bf_lo(xw.x), bf_hi(xw.x), bf_lo(xw.y), bf_hi(xw.y)} + acc[ai][bj][m][0], v1 = (f32x4){bf_lo(xw.z), bf_hi(xw.z), bf_lo(xw.w), bf_hi(xw.w)} + acc[ai][bj][m][1];
;                 ss += (v0[0] * v0[0] + v0[1] * v0[1]) + (v0[2] * v0[2] + v0[3] * v0[3]) + (v1[0] * v1[0] + v1[1] * v1[1]) + (v1[2] * v1[2] + v1[3] * v1[3]);
;                 *(u32x4*)(orow + bj * HALF) = pack8(v0, v1);
;             }
;             ss += __shfl_xor(ss, 16); ss += __shfl_xor(ss, 32);
;             if (fq == 0) atomic_addf(ssq3 + row, ss);
; #pragma unroll
;             for (int q = 0; q < 2; ++q) xc[q] = xn[q];
;             __builtin_amdgcn_sched_barrier(0);
;         }
.LBB0_1155:
	s_or_b64 exec, exec, s[24:25]
	v_add_co_u32_e32 v32, vcc, 0xb0000, v154
	v_lshlrev_b32_e32 v44, 16, v52
	s_waitcnt lgkmcnt(0)
	v_addc_co_u32_e32 v33, vcc, 0, v155, vcc
	v_mov_b32_e32 v36, v228
	v_mov_b32_e32 v37, v229
	v_mov_b32_e32 v38, v230
	v_mov_b32_e32 v39, v231
	v_mov_b32_e32 v32, v232
	v_mov_b32_e32 v33, v233
	v_mov_b32_e32 v34, v234
	v_mov_b32_e32 v35, v235
	v_and_b32_e32 v45, 0xffff0000, v52
	v_lshlrev_b32_e32 v46, 16, v53
	v_and_b32_e32 v47, 0xffff0000, v53
	v_pk_add_f32 v[30:31], v[30:31], v[46:47]
	v_pk_add_f32 v[28:29], v[28:29], v[44:45]
	v_lshlrev_b32_e32 v44, 16, v54
	v_and_b32_e32 v45, 0xffff0000, v54
	v_lshlrev_b32_e32 v46, 16, v55
	v_and_b32_e32 v47, 0xffff0000, v55
	v_pk_add_f32 v[46:47], v[26:27], v[46:47]
	v_pk_add_f32 v[26:27], v[24:25], v[44:45]
	v_mul_f32_e32 v24, v29, v29
	v_mul_f32_e32 v25, v31, v31
	v_fmac_f32_e32 v24, v28, v28
	v_fmac_f32_e32 v25, v30, v30
	v_add_f32_e32 v24, v24, v25
	v_mul_f32_e32 v25, v27, v27
	v_fmac_f32_e32 v25, v26, v26
	v_add_f32_e32 v24, v25, v24
	v_mul_f32_e32 v25, v47, v47
	v_fmac_f32_e32 v25, v46, v46
	v_add_f32_e32 v44, v25, v24
	v_cvt_pk_bf16_f32 v24, v28, v29
	v_cvt_pk_bf16_f32 v25, v30, v31
	v_lshlrev_b32_e32 v28, 16, v48
	v_and_b32_e32 v29, 0xffff0000, v48
	v_lshlrev_b32_e32 v30, 16, v49
	v_and_b32_e32 v31, 0xffff0000, v49
	v_pk_add_f32 v[22:23], v[22:23], v[30:31]
	v_pk_add_f32 v[20:21], v[20:21], v[28:29]
	v_lshlrev_b32_e32 v28, 16, v50
	v_and_b32_e32 v29, 0xffff0000, v50
	v_pk_add_f32 v[28:29], v[16:17], v[28:29]
	v_mul_f32_e32 v16, v21, v21
	v_mul_f32_e32 v17, v23, v23
	v_fmac_f32_e32 v16, v20, v20
	v_fmac_f32_e32 v17, v22, v22
	v_lshlrev_b32_e32 v30, 16, v51
	v_and_b32_e32 v31, 0xffff0000, v51
	v_add_f32_e32 v16, v16, v17
	v_mul_f32_e32 v17, v29, v29
	v_pk_add_f32 v[30:31], v[18:19], v[30:31]
	v_fmac_f32_e32 v17, v28, v28
	v_add_f32_e32 v16, v17, v16
	v_mul_f32_e32 v17, v31, v31
	v_fmac_f32_e32 v17, v30, v30
	v_add_f32_e32 v16, v17, v16
	v_add_f32_e32 v16, v44, v16
	ds_bpermute_b32 v17, v165, v16
	v_or_b32_e32 v40, 32, v72
	v_ashrrev_i32_e32 v41, 31, v40
	v_lshlrev_b64 v[42:43], 12, v[40:41]
	v_lshl_add_u64 v[42:43], s[26:27], 0, v[42:43]
	s_waitcnt lgkmcnt(0)
	v_add_f32_e32 v16, v16, v17
	ds_bpermute_b32 v17, v122, v16
	v_lshl_add_u64 v[42:43], v[152:153], 1, v[42:43]
	v_cvt_pk_bf16_f32 v26, v26, v27
	v_cvt_pk_bf16_f32 v27, v46, v47
	global_store_dwordx4 v[42:43], v[24:27], off
	v_cvt_pk_bf16_f32 v18, v20, v21
	v_cvt_pk_bf16_f32 v19, v22, v23
	v_cvt_pk_bf16_f32 v20, v28, v29
	v_cvt_pk_bf16_f32 v21, v30, v31
	global_store_dwordx4 v[42:43], v[18:21], off offset:256
	s_and_saveexec_b64 s[24:25], s[2:3]
	s_cbranch_execz .LBB0_1157
	s_waitcnt lgkmcnt(0)
	v_add_f32_e32 v18, v16, v17
	v_lshl_add_u64 v[16:17], v[40:41], 2, s[6:7]
	global_atomic_add_f32 v[16:17], v18, off
.LBB0_1157:
	s_or_b64 exec, exec, s[24:25]
	v_lshlrev_b32_e32 v20, 16, v36
	v_and_b32_e32 v21, 0xffff0000, v36
	v_lshlrev_b32_e32 v22, 16, v37
	v_and_b32_e32 v23, 0xffff0000, v37
	v_pk_add_f32 v[14:15], v[14:15], v[22:23]
	v_pk_add_f32 v[12:13], v[12:13], v[20:21]
	v_lshlrev_b32_e32 v20, 16, v38
	v_and_b32_e32 v21, 0xffff0000, v38
	v_lshlrev_b32_e32 v22, 16, v39
	v_and_b32_e32 v23, 0xffff0000, v39
	v_pk_add_f32 v[22:23], v[10:11], v[22:23]
	v_pk_add_f32 v[10:11], v[8:9], v[20:21]
	v_mul_f32_e32 v8, v13, v13
	v_mul_f32_e32 v9, v15, v15
	v_fmac_f32_e32 v8, v12, v12
	v_fmac_f32_e32 v9, v14, v14
	v_add_f32_e32 v8, v8, v9
	v_mul_f32_e32 v9, v11, v11
	v_fmac_f32_e32 v9, v10, v10
	v_add_f32_e32 v8, v9, v8
	v_mul_f32_e32 v9, v23, v23
	v_fmac_f32_e32 v9, v22, v22
	v_add_f32_e32 v20, v9, v8
	v_cvt_pk_bf16_f32 v8, v12, v13
	v_cvt_pk_bf16_f32 v9, v14, v15
	v_lshlrev_b32_e32 v12, 16, v32
	v_and_b32_e32 v13, 0xffff0000, v32
	v_lshlrev_b32_e32 v14, 16, v33
	v_and_b32_e32 v15, 0xffff0000, v33
	v_pk_add_f32 v[6:7], v[6:7], v[14:15]
	v_pk_add_f32 v[4:5], v[4:5], v[12:13]
	v_lshlrev_b32_e32 v12, 16, v34
	v_and_b32_e32 v13, 0xffff0000, v34
	v_pk_add_f32 v[12:13], v[0:1], v[12:13]
	v_mul_f32_e32 v0, v5, v5
	v_mul_f32_e32 v1, v7, v7
	v_fmac_f32_e32 v0, v4, v4
	v_fmac_f32_e32 v1, v6, v6
	v_lshlrev_b32_e32 v14, 16, v35
	v_and_b32_e32 v15, 0xffff0000, v35
	v_add_f32_e32 v0, v0, v1
	v_mul_f32_e32 v1, v13, v13
	v_pk_add_f32 v[14:15], v[2:3], v[14:15]
	v_fmac_f32_e32 v1, v12, v12
	v_add_f32_e32 v0, v1, v0
	v_mul_f32_e32 v1, v15, v15
	v_fmac_f32_e32 v1, v14, v14
	v_add_f32_e32 v0, v1, v0
	v_add_f32_e32 v0, v20, v0
	ds_bpermute_b32 v1, v165, v0
	v_or_b32_e32 v16, 48, v72
	s_waitcnt lgkmcnt(1)
	v_ashrrev_i32_e32 v17, 31, v16
	v_lshlrev_b64 v[18:19], 12, v[16:17]
	v_lshl_add_u64 v[18:19], s[26:27], 0, v[18:19]
	s_waitcnt lgkmcnt(0)
	v_add_f32_e32 v0, v0, v1
	ds_bpermute_b32 v1, v122, v0
	v_lshl_add_u64 v[18:19], v[152:153], 1, v[18:19]
	v_cvt_pk_bf16_f32 v10, v10, v11
	v_cvt_pk_bf16_f32 v11, v22, v23
	global_store_dwordx4 v[18:19], v[8:11], off
	v_cvt_pk_bf16_f32 v2, v4, v5
	v_cvt_pk_bf16_f32 v3, v6, v7
	v_cvt_pk_bf16_f32 v4, v12, v13
	v_cvt_pk_bf16_f32 v5, v14, v15
	global_store_dwordx4 v[18:19], v[2:5], off offset:256
	s_and_saveexec_b64 s[24:25], s[2:3]
	s_cbranch_execz .LBB0_1159
	s_waitcnt lgkmcnt(0)
	v_add_f32_e32 v2, v0, v1
	v_lshl_add_u64 v[0:1], v[16:17], 2, s[6:7]
	global_atomic_add_f32 v[0:1], v2, off
